# grid-barrier wake-up: on a poll hit the cache invalidate is issued at once, the still-outstanding polls drain under it
# speedup vs baseline: 1.0050x; 1.0023x over previous
; __device__ __forceinline__ unsigned xb_ld(unsigned* p)              { return __hip_atomic_load(p, __ATOMIC_RELAXED, __HIP_MEMORY_SCOPE_AGENT); }
; #define XB_SPIN(cond, bar) do { unsigned _sp = 0; while (cond) { __builtin_amdgcn_s_sleep(1); \
;     if ((++_sp & 255u) == 0u) { if (xb_ld(&(bar)[XB_TMO])) break; if (_sp > XB_SPIN_CAP) { atomicAdd(&(bar)[XB_TMO], 1u); break; } } } } while (0)
; __device__ __forceinline__ void xcd_barrier(const XcdBarrier& b) {
;     ...
;         XB_SPIN(xb_ld(&bar[XB_XGEN(bx_)]) < (gen + 1u) * nx, bar);
;         __builtin_amdgcn_fence(__ATOMIC_ACQUIRE, "agent");
;         asm volatile("s_waitcnt vmcnt(0)" ::: "memory");
.Lpp0_hit:
	buffer_inv sc1
	s_waitcnt vmcnt(0)
	s_branch .LBB0_742
